# prompt attention: partialSM row-max chain moved into the shadow of the last PV MFMAs on unmasked tiles (both half-steps); mask test hoisted
# baseline (speedup 1.0000x reference)
; __device__ __forceinline__ void finishSM(f32x16& p0, f32x16& p1, float alpha, float& l_reg, bf16x8& pa0, bf16x8& pa1, bf16x8& pa2, bf16x8& pa3) {
;     for (int r = 0; r < 16; ++r) p1[r] = __builtin_amdgcn_exp2f(p1[r]);
;     float ps = 0; for (int r = 0; r < 16; ++r) ps += p0[r]; for (int r = 0; r < 16; ++r) ps += p1[r];
;     { auto rr = __builtin_amdgcn_permlane32_swap(__float_as_uint(ps), __float_as_uint(ps), false, false);
;       ps = __uint_as_float(rr[0]) + __uint_as_float(rr[1]); }
;     l_reg = l_reg * alpha + ps;
;     ...
;     PK4(p0, 0, pa0); PK4(p0, 8, pa1); PK4(p1, 0, pa2); PK4(p1, 8, pa3);
;     ...
; }
; template <int KB, bool SK>
; __device__ __forceinline__ void qkt(f32x16& p0, f32x16& p1, const char* K_lds, const float* B_lds, int r32, int hi, const bf16x8* qr, bool act) {
;     if (SK && !act) { const float NEG = -__builtin_inff();
; #pragma unroll
;         for (int r = 0; r < 16; ++r) { p0[r] = NEG; p1[r] = NEG; } return; }
;     ...
;     p0 = f32x16{}; p1 = f32x16{};
;     ...
;     p0 = *(const f32x16*)(B_lds + KB * 64 + hi * 32); p1 = *(const f32x16*)(B_lds + KB * 64 + hi * 32 + 16);
;     ...
;     const char* kb[4];
; #pragma unroll
;     for (int dd = 0; dd < 4; ++dd) kb[dd] = K_lds + KB * SHM_K + KSWZ(r32, (dd * 16 + hi * 8) * 2);
; #pragma unroll
;     for (int d0 = 0; d0 < 8; ++d0) { const char* a = kb[d0 & 3] + (d0 >> 2) * 128;
;         bf16x8 b0 = *reinterpret_cast<const bf16x8*>(a);
;         bf16x8 b1 = *reinterpret_cast<const bf16x8*>(a + 32 * 256);
;         p0 = __builtin_amdgcn_mfma_f32_32x32x16_bf16(b0, qr[d0], p0, 0, 0, 0);
;         p1 = __builtin_amdgcn_mfma_f32_32x32x16_bf16(b1, qr[d0], p1, 0, 0, 0); }
; }
.LBB0_1247:
	v_add_u32_e32 v200, v230, v219
	v_add_u32_e32 v248, s68, v200
	v_add_u32_e32 v200, 1, v248
	v_lshl_add_u64 v[2:3], v[200:201], 2, s[66:67]
	v_mov_b32_e32 v15, v1
	v_add_u32_e32 v200, 0x10000, v14
	v_lshlrev_b64 v[10:11], 1, v[14:15]
	v_lshlrev_b64 v[12:13], 1, v[200:201]
	global_load_dword v246, v[2:3], off
	v_lshl_add_u64 v[2:3], s[64:65], 0, v[10:11]
	v_lshl_add_u64 v[6:7], s[64:65], 0, v[12:13]
	v_lshl_add_u64 v[10:11], s[62:63], 0, v[10:11]
	global_load_dwordx4 v[2:5], v[2:3], off
	s_nop 0
	global_load_dwordx4 v[6:9], v[6:7], off
	v_lshl_add_u64 v[210:211], s[62:63], 0, v[12:13]
	global_load_dwordx4 v[10:13], v[10:11], off
	s_nop 0
	global_load_dwordx4 v[210:213], v[210:211], off
	v_add_u32_e32 v0, 0x10900, v236
	ds_read_b128 v[100:103], v0
	ds_read_b128 v[104:107], v0 offset:16
	ds_read_b128 v[108:111], v0 offset:32
	s_waitcnt vmcnt(7)
	ds_read_b128 v[112:115], v0 offset:48
	ds_read_b128 v[96:99], v0 offset:112
	ds_read_b128 v[92:95], v0 offset:96
	ds_read_b128 v[88:91], v0 offset:80
	ds_read_b128 v[84:87], v0 offset:64
	ds_read_b128 v[202:205], v235 offset:49152
	ds_read_b128 v[206:209], v235 offset:57344
	v_add_f32_e32 v80, 0, v191
	v_add_f32_e32 v80, v193, v80
	v_add_f32_e32 v80, v189, v80
	s_waitcnt lgkmcnt(1)
	v_mfma_f32_32x32x16_bf16 v[100:115], v[202:205], v[172:175], v[100:115]
	v_add_f32_e32 v80, v192, v80
	v_add_f32_e32 v80, v188, v80
	v_add_f32_e32 v80, v190, v80
	v_add_f32_e32 v80, v186, v80
	v_add_f32_e32 v80, v187, v80
	v_add_f32_e32 v80, v182, v80
	v_add_f32_e32 v80, v185, v80
	s_waitcnt lgkmcnt(0)
	v_mfma_f32_32x32x16_bf16 v[84:99], v[206:209], v[172:175], v[84:99]
	ds_read_b128 v[202:205], v234 offset:49152
	ds_read_b128 v[206:209], v234 offset:57344
	v_add_f32_e32 v80, v179, v80
	v_add_f32_e32 v80, v183, v80
	v_exp_f32_e32 v0, v142
	v_add_f32_e32 v80, v177, v80
	v_add_f32_e32 v80, v184, v80
	v_add_f32_e32 v80, v178, v80
	s_waitcnt lgkmcnt(1)
	v_mfma_f32_32x32x16_bf16 v[100:115], v[202:205], v[168:171], v[100:115]
	v_add_f32_e32 v80, v181, v80
	v_add_f32_e32 v80, v0, v80
	v_exp_f32_e32 v194, v135
	v_exp_f32_e32 v195, v132
	v_exp_f32_e32 v196, v133
	v_exp_f32_e32 v197, v130
	v_exp_f32_e32 v198, v131
	s_waitcnt lgkmcnt(0)
	v_mfma_f32_32x32x16_bf16 v[84:99], v[206:209], v[168:171], v[84:99]
	ds_read_b128 v[202:205], v233 offset:49152
	ds_read_b128 v[206:209], v233 offset:57344
	v_exp_f32_e32 v127, v128
	v_exp_f32_e32 v128, v129
	s_sub_i32 s4, s68, 63
	s_waitcnt lgkmcnt(1)
	v_mfma_f32_32x32x16_bf16 v[100:115], v[202:205], v[164:167], v[100:115]
	s_waitcnt lgkmcnt(0)
	v_mfma_f32_32x32x16_bf16 v[84:99], v[206:209], v[164:167], v[84:99]
	ds_read_b128 v[202:205], v232 offset:49152
	ds_read_b128 v[206:209], v232 offset:57344
	s_waitcnt lgkmcnt(1)
	v_mfma_f32_32x32x16_bf16 v[100:115], v[202:205], v[160:163], v[100:115]
	s_waitcnt lgkmcnt(0)
	v_mfma_f32_32x32x16_bf16 v[84:99], v[206:209], v[160:163], v[84:99]
	ds_read_b128 v[202:205], v235 offset:49280
	ds_read_b128 v[206:209], v235 offset:57472
	s_waitcnt lgkmcnt(1)
	v_mfma_f32_32x32x16_bf16 v[100:115], v[202:205], v[156:159], v[100:115]
	s_waitcnt lgkmcnt(0)
	v_mfma_f32_32x32x16_bf16 v[84:99], v[206:209], v[156:159], v[84:99]
	ds_read_b128 v[202:205], v234 offset:49280
	ds_read_b128 v[206:209], v234 offset:57472
	s_waitcnt lgkmcnt(1)
	v_mfma_f32_32x32x16_bf16 v[100:115], v[202:205], v[152:155], v[100:115]
	s_waitcnt lgkmcnt(0)
	v_mfma_f32_32x32x16_bf16 v[84:99], v[206:209], v[152:155], v[84:99]
	ds_read_b128 v[202:205], v233 offset:49280
	ds_read_b128 v[206:209], v233 offset:57472
	s_waitcnt lgkmcnt(1)
	v_mfma_f32_32x32x16_bf16 v[100:115], v[202:205], v[148:151], v[100:115]
	s_waitcnt lgkmcnt(0)
	v_mfma_f32_32x32x16_bf16 v[84:99], v[206:209], v[148:151], v[84:99]
	ds_read_b128 v[202:205], v232 offset:49280
	ds_read_b128 v[206:209], v232 offset:57472
	s_waitcnt lgkmcnt(1)
	v_mfma_f32_32x32x16_bf16 v[100:115], v[202:205], v[144:147], v[100:115]
	v_exp_f32_e32 v202, v143
	v_exp_f32_e32 v203, v140
	v_exp_f32_e32 v204, v141
	v_exp_f32_e32 v205, v138
	v_add_f32_e32 v80, v202, v80
	v_add_f32_e32 v80, v203, v80
	v_add_f32_e32 v80, v204, v80
	s_waitcnt lgkmcnt(0)
	v_mfma_f32_32x32x16_bf16 v[84:99], v[206:209], v[144:147], v[84:99]
	v_exp_f32_e32 v206, v139
	v_exp_f32_e32 v207, v136
	v_exp_f32_e32 v208, v137
	v_exp_f32_e32 v209, v134
	v_add_f32_e32 v80, v205, v80
	v_add_f32_e32 v80, v206, v80
	v_add_f32_e32 v80, v207, v80
	v_add_f32_e32 v80, v208, v80
	v_add_f32_e32 v80, v209, v80
	v_add_f32_e32 v80, v194, v80
	v_add_f32_e32 v80, v195, v80
	v_add_f32_e32 v80, v196, v80
	v_add_f32_e32 v80, v197, v80
	v_add_f32_e32 v80, v198, v80
	v_add_f32_e32 v80, v127, v80
	v_add_f32_e32 v244, v128, v80
	v_mov_b32_e32 v245, v244
	s_nop 1
	v_permlane32_swap_b32_e32 v244, v245
	v_cvt_pk_bf16_f32 v80, v191, v193
	v_cvt_pk_bf16_f32 v81, v189, v192
	v_cvt_pk_bf16_f32 v82, v188, v190
	v_cvt_pk_bf16_f32 v83, v186, v187
	s_waitcnt vmcnt(6)
	v_cvt_pk_bf16_f32 v116, v182, v185
	v_cvt_pk_bf16_f32 v117, v179, v183
	v_cvt_pk_bf16_f32 v118, v177, v184
	v_cvt_pk_bf16_f32 v119, v178, v181
	s_waitcnt vmcnt(5)
	v_cvt_pk_bf16_f32 v120, v0, v202
	v_cvt_pk_bf16_f32 v121, v203, v204
	v_cvt_pk_bf16_f32 v122, v205, v206
	v_cvt_pk_bf16_f32 v123, v207, v208
	v_cvt_pk_bf16_f32 v124, v209, v194
	v_cvt_pk_bf16_f32 v125, v195, v196
	v_cvt_pk_bf16_f32 v126, v197, v198
	v_cvt_pk_bf16_f32 v127, v127, v128
	v_permlane32_swap_b32_e32 v80, v82
	v_permlane32_swap_b32_e32 v81, v83
	v_permlane32_swap_b32_e32 v116, v118
	v_permlane32_swap_b32_e32 v117, v119
	v_permlane32_swap_b32_e32 v120, v122
	v_permlane32_swap_b32_e32 v121, v123
	v_permlane32_swap_b32_e32 v124, v126
	v_permlane32_swap_b32_e32 v125, v127
	ds_read_b64_tr_b16 v[128:129], v227 offset:0
	ds_read_b64_tr_b16 v[130:131], v227 offset:0x800
	ds_read_b64_tr_b16 v[132:133], v227 offset:0x1000
	ds_read_b64_tr_b16 v[134:135], v227 offset:0x1800
	ds_read_b64_tr_b16 v[136:137], v227 offset:0x2000
	ds_read_b64_tr_b16 v[138:139], v227 offset:0x2800
	ds_read_b64_tr_b16 v[140:141], v227 offset:0x3000
	ds_read_b64_tr_b16 v[142:143], v227 offset:0x3800
	s_waitcnt lgkmcnt(0)
; __device__ __forceinline__ void partialSM(f32x16& p0, f32x16& p1, float& m_reg, float& mn, float& alpha) {
;     float pmax = p0[0]; for (int r = 1; r < 16; ++r) pmax = fmaxf(pmax, p0[r]); for (int r = 0; r < 16; ++r) pmax = fmaxf(pmax, p1[r]);
;     { auto rr = __builtin_amdgcn_permlane32_swap(__float_as_uint(pmax), __float_as_uint(pmax), false, false);
;       pmax = fmaxf(__uint_as_float(rr[0]), __uint_as_float(rr[1])); }
;     constexpr float C2 = 1.4426950408889634f * SCALE;
;     if (__builtin_expect(__all((pmax - m_reg) * SCALE <= THR), 1)) { mn = m_reg; alpha = 1.f; }
;     else { mn = fmaxf(m_reg, pmax); alpha = __builtin_amdgcn_exp2f((m_reg - mn) * C2); m_reg = mn; }
; template <int VB, bool SK>
; __device__ __forceinline__ void pv_tile(f32x16* o, int vb0, bf16x8 pa0, bf16x8 pa1, bf16x8 pa2, bf16x8 pa3, bool act) {
;     if (SK && !act) return;
;     ...
;     PV_D0(0); PV_D0(1); PV_D0(2); PV_D0(3);
	s_nop 0
	v_mfma_f32_32x32x16_bf16 v[64:79], v[80:83], v[128:131], v[64:79]
	ds_read_b64_tr_b16 v[128:129], v227 offset:0x200
	ds_read_b64_tr_b16 v[130:131], v227 offset:0xa00
	v_mfma_f32_32x32x16_bf16 v[64:79], v[116:119], v[132:135], v[64:79]
	ds_read_b64_tr_b16 v[132:133], v227 offset:0x1200
	ds_read_b64_tr_b16 v[134:135], v227 offset:0x1a00
	v_mfma_f32_32x32x16_bf16 v[64:79], v[120:123], v[136:139], v[64:79]
	ds_read_b64_tr_b16 v[136:137], v227 offset:0x2200
	ds_read_b64_tr_b16 v[138:139], v227 offset:0x2a00
	v_mfma_f32_32x32x16_bf16 v[64:79], v[124:127], v[140:143], v[64:79]
	ds_read_b64_tr_b16 v[140:141], v227 offset:0x3200
	ds_read_b64_tr_b16 v[142:143], v227 offset:0x3a00
	s_waitcnt lgkmcnt(0)
	v_mfma_f32_32x32x16_bf16 v[48:63], v[80:83], v[128:131], v[48:63]
	ds_read_b64_tr_b16 v[128:129], v227 offset:0x400
	ds_read_b64_tr_b16 v[130:131], v227 offset:0xc00
	v_mfma_f32_32x32x16_bf16 v[48:63], v[116:119], v[132:135], v[48:63]
	ds_read_b64_tr_b16 v[132:133], v227 offset:0x1400
	ds_read_b64_tr_b16 v[134:135], v227 offset:0x1c00
	v_mfma_f32_32x32x16_bf16 v[48:63], v[120:123], v[136:139], v[48:63]
	ds_read_b64_tr_b16 v[136:137], v227 offset:0x2400
	ds_read_b64_tr_b16 v[138:139], v227 offset:0x2c00
	v_mfma_f32_32x32x16_bf16 v[48:63], v[124:127], v[140:143], v[48:63]
	ds_read_b64_tr_b16 v[140:141], v227 offset:0x3400
	ds_read_b64_tr_b16 v[142:143], v227 offset:0x3c00
	s_waitcnt lgkmcnt(0)
	s_cmp_le_i32 s68, s57
	s_cselect_b64 s[28:29], -1, 0
	s_cmp_gt_i32 s4, s58
	s_cselect_b64 s[4:5], -1, 0
	s_and_b64 s[4:5], s[28:29], s[4:5]
	s_and_b64 vcc, exec, s[4:5]
	s_cbranch_vccz .Lattn_h1_pv_slow
	v_mfma_f32_32x32x16_bf16 v[32:47], v[80:83], v[128:131], v[32:47]
	ds_read_b64_tr_b16 v[128:129], v227 offset:0x600
	ds_read_b64_tr_b16 v[130:131], v227 offset:0xe00
	v_max_f32_e32 v0, v101, v101
	v_max_f32_e32 v15, v100, v100
	v_mfma_f32_32x32x16_bf16 v[32:47], v[116:119], v[132:135], v[32:47]
	ds_read_b64_tr_b16 v[132:133], v227 offset:0x1600
	ds_read_b64_tr_b16 v[134:135], v227 offset:0x1e00
	v_max_f32_e32 v0, v15, v0
	v_max3_f32 v0, v0, v102, v103
	v_max3_f32 v0, v0, v104, v105
	v_mfma_f32_32x32x16_bf16 v[32:47], v[120:123], v[136:139], v[32:47]
	ds_read_b64_tr_b16 v[136:137], v227 offset:0x2600
	ds_read_b64_tr_b16 v[138:139], v227 offset:0x2e00
	v_max3_f32 v0, v0, v106, v107
	v_max3_f32 v0, v0, v108, v109
	v_max3_f32 v0, v0, v110, v111
	v_mfma_f32_32x32x16_bf16 v[32:47], v[124:127], v[140:143], v[32:47]
	ds_read_b64_tr_b16 v[140:141], v227 offset:0x3600
	ds_read_b64_tr_b16 v[142:143], v227 offset:0x3e00
	v_max3_f32 v0, v0, v112, v113
	v_max3_f32 v0, v0, v114, v115
	v_max3_f32 v0, v0, v84, v85
	s_waitcnt lgkmcnt(0)
	v_mfma_f32_32x32x16_bf16 v[16:31], v[80:83], v[128:131], v[16:31]
	v_max3_f32 v0, v0, v86, v87
	v_max3_f32 v0, v0, v88, v89
	v_max3_f32 v0, v0, v90, v91
	v_mfma_f32_32x32x16_bf16 v[16:31], v[116:119], v[132:135], v[16:31]
	v_max3_f32 v0, v0, v92, v93
	v_max3_f32 v0, v0, v94, v95
	v_max3_f32 v0, v0, v96, v97
	v_max3_f32 v0, v0, v98, v99
	v_mov_b32_e32 v15, v0
	v_mfma_f32_32x32x16_bf16 v[16:31], v[120:123], v[136:139], v[16:31]
	s_nop 0
	v_permlane32_swap_b32_e32 v0, v15
	v_max_f32_e32 v15, v15, v15
	v_max_f32_e32 v0, v0, v0
	v_max_f32_e32 v0, v0, v15
	v_mfma_f32_32x32x16_bf16 v[16:31], v[124:127], v[140:143], v[16:31]
	v_sub_f32_e32 v15, v0, v180
	v_mul_f32_e32 v15, 0x3db504f3, v15
	v_cmp_ge_f32_e32 vcc, s83, v15
	v_max_f32_e32 v15, v180, v180
	v_max_f32_e32 v0, v15, v0
	v_sub_f32_e32 v15, v180, v0
	v_mul_f32_e32 v15, 0x3e0293ee, v15
	v_exp_f32_e32 v15, v15
	s_cmp_eq_u64 vcc, exec
	s_cselect_b64 s[4:5], -1, 0
	s_branch .Lattn_h1_b1
; __device__ __forceinline__ void mask_tile(f32x16& p0, f32x16& p1, int dq, unsigned W) {
;     const float NEG = -__builtin_inff();
; #pragma unroll
;     for (int r = 0; r < 16; ++r) {
;         const int c = (r & 3) + 8 * (r >> 2);
;         if ((unsigned)(dq - c) >= W) p0[r] = NEG;
;         if ((unsigned)(dq - c - 32) >= W) p1[r] = NEG;
;     }
; }
; template <int VB, bool SK>
; __device__ __forceinline__ void pv_tile(f32x16* o, int vb0, bf16x8 pa0, bf16x8 pa1, bf16x8 pa2, bf16x8 pa3, bool act) {
;     if (SK && !act) return;
;     ...
;     PV_D0(0); PV_D0(1); PV_D0(2); PV_D0(3);
.Lattn_h1_pv_slow:
	v_mfma_f32_32x32x16_bf16 v[32:47], v[80:83], v[128:131], v[32:47]
	ds_read_b64_tr_b16 v[128:129], v227 offset:0x600
	ds_read_b64_tr_b16 v[130:131], v227 offset:0xe00
	v_mfma_f32_32x32x16_bf16 v[32:47], v[116:119], v[132:135], v[32:47]
	ds_read_b64_tr_b16 v[132:133], v227 offset:0x1600
	ds_read_b64_tr_b16 v[134:135], v227 offset:0x1e00
	v_mfma_f32_32x32x16_bf16 v[32:47], v[120:123], v[136:139], v[32:47]
	ds_read_b64_tr_b16 v[136:137], v227 offset:0x2600
	ds_read_b64_tr_b16 v[138:139], v227 offset:0x2e00
	v_mfma_f32_32x32x16_bf16 v[32:47], v[124:127], v[140:143], v[32:47]
	ds_read_b64_tr_b16 v[140:141], v227 offset:0x3600
	ds_read_b64_tr_b16 v[142:143], v227 offset:0x3e00
	s_waitcnt lgkmcnt(0)
	v_mfma_f32_32x32x16_bf16 v[16:31], v[80:83], v[128:131], v[16:31]
	v_mfma_f32_32x32x16_bf16 v[16:31], v[116:119], v[132:135], v[16:31]
	v_mfma_f32_32x32x16_bf16 v[16:31], v[120:123], v[136:139], v[16:31]
	v_mfma_f32_32x32x16_bf16 v[16:31], v[124:127], v[140:143], v[16:31]
	v_add_u32_e32 v0, 0x107b, v243
	v_cmp_gt_u32_e32 vcc, s81, v0
	v_add_u32_e32 v0, 0x5b, v243
	s_nop 0
	v_cndmask_b32_e32 v100, v216, v100, vcc
	v_cmp_lt_u32_e32 vcc, s82, v0
	v_add_u32_e32 v0, 0x7a, v243
	s_nop 0
	v_cndmask_b32_e32 v84, v216, v84, vcc
	v_cmp_lt_u32_e32 vcc, s82, v0
	v_add_u32_e32 v0, 0x5a, v243
	s_nop 0
	v_cndmask_b32_e32 v101, v216, v101, vcc
	v_cmp_lt_u32_e32 vcc, s82, v0
	v_add_u32_e32 v0, 0x79, v243
	s_nop 0
	v_cndmask_b32_e32 v85, v216, v85, vcc
	v_cmp_lt_u32_e32 vcc, s82, v0
	v_add_u32_e32 v0, 0x59, v243
	s_nop 0
	v_cndmask_b32_e32 v102, v216, v102, vcc
	v_cmp_lt_u32_e32 vcc, s82, v0
	v_add_u32_e32 v0, 0x78, v243
	s_nop 0
	v_cndmask_b32_e32 v86, v216, v86, vcc
	v_cmp_lt_u32_e32 vcc, s82, v0
	v_add_u32_e32 v0, 0x58, v243
	s_nop 0
	v_cndmask_b32_e32 v103, v216, v103, vcc
	v_cmp_lt_u32_e32 vcc, s82, v0
	v_add_u32_e32 v0, 0x73, v243
	s_nop 0
	v_cndmask_b32_e32 v87, v216, v87, vcc
	v_cmp_lt_u32_e32 vcc, s82, v0
	v_add_u32_e32 v0, 0x53, v243
	s_nop 0
	v_cndmask_b32_e32 v104, v216, v104, vcc
	v_cmp_lt_u32_e32 vcc, s82, v0
	v_add_u32_e32 v0, 0x72, v243
	s_nop 0
	v_cndmask_b32_e32 v88, v216, v88, vcc
	v_cmp_lt_u32_e32 vcc, s82, v0
	v_add_u32_e32 v0, 0x52, v243
	s_nop 0
	v_cndmask_b32_e32 v105, v216, v105, vcc
	v_cmp_lt_u32_e32 vcc, s82, v0
	v_add_u32_e32 v0, 0x71, v243
	s_nop 0
	v_cndmask_b32_e32 v89, v216, v89, vcc
	v_cmp_lt_u32_e32 vcc, s82, v0
	v_add_u32_e32 v0, 0x51, v243
	s_nop 0
	v_cndmask_b32_e32 v106, v216, v106, vcc
	v_cmp_lt_u32_e32 vcc, s82, v0
	v_add_u32_e32 v0, 0x70, v243
	s_nop 0
	v_cndmask_b32_e32 v90, v216, v90, vcc
	v_cmp_lt_u32_e32 vcc, s82, v0
	v_add_u32_e32 v0, 0x50, v243
	s_nop 0
	v_cndmask_b32_e32 v107, v216, v107, vcc
	v_cmp_lt_u32_e32 vcc, s82, v0
	v_add_u32_e32 v0, 0x6b, v243
	s_nop 0
	v_cndmask_b32_e32 v91, v216, v91, vcc
	v_cmp_lt_u32_e32 vcc, s82, v0
	v_add_u32_e32 v0, 0x4b, v243
	s_nop 0
	v_cndmask_b32_e32 v108, v216, v108, vcc
	v_cmp_lt_u32_e32 vcc, s82, v0
	v_add_u32_e32 v0, 0x6a, v243
	s_nop 0
	v_cndmask_b32_e32 v92, v216, v92, vcc
	v_cmp_lt_u32_e32 vcc, s82, v0
	v_add_u32_e32 v0, 0x4a, v243
	s_nop 0
	v_cndmask_b32_e32 v109, v216, v109, vcc
	v_cmp_lt_u32_e32 vcc, s82, v0
	v_add_u32_e32 v0, 0x69, v243
	s_nop 0
	v_cndmask_b32_e32 v93, v216, v93, vcc
	v_cmp_lt_u32_e32 vcc, s82, v0
	v_add_u32_e32 v0, 0x49, v243
	s_nop 0
	v_cndmask_b32_e32 v110, v216, v110, vcc
	v_cmp_lt_u32_e32 vcc, s82, v0
	v_add_u32_e32 v0, 0x68, v243
	s_nop 0
	v_cndmask_b32_e32 v94, v216, v94, vcc
	v_cmp_lt_u32_e32 vcc, s82, v0
	v_add_u32_e32 v0, 0x48, v243
	s_nop 0
	v_cndmask_b32_e32 v111, v216, v111, vcc
	v_cmp_lt_u32_e32 vcc, s82, v0
	v_add_u32_e32 v0, 0x63, v243
	s_nop 0
	v_cndmask_b32_e32 v95, v216, v95, vcc
	v_cmp_lt_u32_e32 vcc, s82, v0
	v_add_u32_e32 v0, 0x43, v243
	s_nop 0
	v_cndmask_b32_e32 v112, v216, v112, vcc
	v_cmp_lt_u32_e32 vcc, s82, v0
	v_add_u32_e32 v0, 0x62, v243
	s_nop 0
	v_cndmask_b32_e32 v96, v216, v96, vcc
	v_cmp_lt_u32_e32 vcc, s82, v0
	v_add_u32_e32 v0, 0x42, v243
	s_nop 0
	v_cndmask_b32_e32 v113, v216, v113, vcc
	v_cmp_lt_u32_e32 vcc, s82, v0
	v_add_u32_e32 v0, 0x61, v243
	s_nop 0
	v_cndmask_b32_e32 v97, v216, v97, vcc
	v_cmp_lt_u32_e32 vcc, s82, v0
	v_add_u32_e32 v0, 0x41, v243
	s_nop 0
	v_cndmask_b32_e32 v114, v216, v114, vcc
	v_cmp_lt_u32_e32 vcc, s82, v0
	v_add_u32_e32 v0, 0x60, v243
	s_nop 0
	v_cndmask_b32_e32 v98, v216, v98, vcc
	v_cmp_lt_u32_e32 vcc, s82, v0
	v_add_u32_e32 v0, 64, v243
	s_nop 0
	v_cndmask_b32_e32 v115, v216, v115, vcc
	v_cmp_lt_u32_e32 vcc, s82, v0
	s_nop 1
	v_cndmask_b32_e32 v99, v216, v99, vcc

.Lattn_h1_b1:
	s_barrier
	s_waitcnt vmcnt(0)
	v_cndmask_b32_e64 v15, v15, 1.0, s[4:5]
	v_cmp_gt_f32_e32 vcc, 1.0, v15
	s_waitcnt vmcnt(3)
	ds_write_b128 v237, v[2:5]
	s_waitcnt vmcnt(2)
	ds_write_b128 v238, v[6:9]
	ds_write_b32 v242, v246
	s_waitcnt vmcnt(1)
	ds_write_b128 v222, v[10:13] offset:32768
	s_waitcnt vmcnt(0)
	ds_write_b128 v222, v[210:213] offset:40960
	s_cbranch_vccz .LBB0_1253
	s_and_saveexec_b64 s[28:29], s[2:3]
	ds_write_b32 v226, v15 offset:128
	s_or_b64 exec, exec, s[28:29]
	s_waitcnt lgkmcnt(0)
	ds_read_b128 v[80:83], v225 offset:224
	ds_read_b128 v[116:119], v225 offset:192
	ds_read_b128 v[120:123], v225 offset:160
	ds_read_b128 v[124:127], v225 offset:128
	s_waitcnt lgkmcnt(3)
	v_pk_mul_f32 v[78:79], v[78:79], v[82:83]
	s_waitcnt lgkmcnt(2)
	v_pk_mul_f32 v[74:75], v[74:75], v[118:119]
	s_waitcnt lgkmcnt(1)
	v_pk_mul_f32 v[70:71], v[70:71], v[122:123]
	s_waitcnt lgkmcnt(0)
	v_pk_mul_f32 v[66:67], v[66:67], v[126:127]
	v_pk_mul_f32 v[76:77], v[76:77], v[80:81]
	v_pk_mul_f32 v[72:73], v[72:73], v[116:117]
	v_pk_mul_f32 v[68:69], v[68:69], v[120:121]
	v_pk_mul_f32 v[64:65], v[64:65], v[124:125]
	v_pk_mul_f32 v[62:63], v[62:63], v[82:83]
	v_pk_mul_f32 v[58:59], v[58:59], v[118:119]
	v_pk_mul_f32 v[54:55], v[54:55], v[122:123]
	v_pk_mul_f32 v[50:51], v[50:51], v[126:127]
	v_pk_mul_f32 v[60:61], v[60:61], v[80:81]
	v_pk_mul_f32 v[56:57], v[56:57], v[116:117]
	v_pk_mul_f32 v[52:53], v[52:53], v[120:121]
	v_pk_mul_f32 v[48:49], v[48:49], v[124:125]
	v_pk_mul_f32 v[46:47], v[46:47], v[82:83]
	v_pk_mul_f32 v[42:43], v[42:43], v[118:119]
	v_pk_mul_f32 v[38:39], v[38:39], v[122:123]
	v_pk_mul_f32 v[34:35], v[34:35], v[126:127]
	v_pk_mul_f32 v[44:45], v[44:45], v[80:81]
	v_pk_mul_f32 v[40:41], v[40:41], v[116:117]
	v_pk_mul_f32 v[36:37], v[36:37], v[120:121]
	v_pk_mul_f32 v[32:33], v[32:33], v[124:125]
	v_pk_mul_f32 v[30:31], v[30:31], v[82:83]
	v_pk_mul_f32 v[26:27], v[26:27], v[118:119]
	v_pk_mul_f32 v[22:23], v[22:23], v[122:123]
	v_pk_mul_f32 v[18:19], v[18:19], v[126:127]
	v_pk_mul_f32 v[28:29], v[28:29], v[80:81]
	v_pk_mul_f32 v[24:25], v[24:25], v[116:117]
	v_pk_mul_f32 v[20:21], v[20:21], v[120:121]
	v_pk_mul_f32 v[16:17], v[16:17], v[124:125]

; __device__ __forceinline__ void partialSM(f32x16& p0, f32x16& p1, float& m_reg, float& mn, float& alpha) {
;     float pmax = p0[0]; for (int r = 1; r < 16; ++r) pmax = fmaxf(pmax, p0[r]); for (int r = 0; r < 16; ++r) pmax = fmaxf(pmax, p1[r]);
;     { auto rr = __builtin_amdgcn_permlane32_swap(__float_as_uint(pmax), __float_as_uint(pmax), false, false);
;       pmax = fmaxf(__uint_as_float(rr[0]), __uint_as_float(rr[1])); }
;     constexpr float C2 = 1.4426950408889634f * SCALE;
;     if (__builtin_expect(__all((pmax - m_reg) * SCALE <= THR), 1)) { mn = m_reg; alpha = 1.f; }
;     else { mn = fmaxf(m_reg, pmax); alpha = __builtin_amdgcn_exp2f((m_reg - mn) * C2); m_reg = mn; }
; template <int VB, bool SK>
; __device__ __forceinline__ void pv_tile(f32x16* o, int vb0, bf16x8 pa0, bf16x8 pa1, bf16x8 pa2, bf16x8 pa3, bool act) {
;     if (SK && !act) return;
;     ...
;     PV_D0(0); PV_D0(1); PV_D0(2); PV_D0(3);
.LBB0_1255:
	ds_read_b64_tr_b16 v[202:203], v227 offset:0x4000
	ds_read_b64_tr_b16 v[204:205], v227 offset:0x4800
	ds_read_b64_tr_b16 v[196:197], v227 offset:0x5000
	ds_read_b64_tr_b16 v[198:199], v227 offset:0x5800
	ds_read_b64_tr_b16 v[210:211], v227 offset:0x6000
	ds_read_b64_tr_b16 v[212:213], v227 offset:0x6800
	ds_read_b64_tr_b16 v[206:207], v227 offset:0x7000
	ds_read_b64_tr_b16 v[208:209], v227 offset:0x7800
	s_waitcnt lgkmcnt(0)
	s_add_i32 s4, s68, 64
	s_add_i32 s69, s68, 1
	v_mfma_f32_32x32x16_bf16 v[64:79], v[180:183], v[202:205], v[64:79]
	v_mfma_f32_32x32x16_bf16 v[64:79], v[184:187], v[196:199], v[64:79]
	ds_read_b64_tr_b16 v[196:197], v227 offset:0x4200
	ds_read_b64_tr_b16 v[198:199], v227 offset:0x4a00
	ds_read_b64_tr_b16 v[202:203], v227 offset:0x5200
	ds_read_b64_tr_b16 v[204:205], v227 offset:0x5a00
	v_mfma_f32_32x32x16_bf16 v[64:79], v[188:191], v[210:213], v[64:79]
	v_mfma_f32_32x32x16_bf16 v[64:79], v[192:195], v[206:209], v[64:79]
	ds_read_b64_tr_b16 v[206:207], v227 offset:0x6200
	ds_read_b64_tr_b16 v[208:209], v227 offset:0x6a00
	ds_read_b64_tr_b16 v[210:211], v227 offset:0x7200
	ds_read_b64_tr_b16 v[212:213], v227 offset:0x7a00
	s_waitcnt lgkmcnt(0)
	v_mfma_f32_32x32x16_bf16 v[48:63], v[180:183], v[196:199], v[48:63]
	ds_read_b64_tr_b16 v[196:197], v227 offset:0x4400
	ds_read_b64_tr_b16 v[198:199], v227 offset:0x4c00
	v_mfma_f32_32x32x16_bf16 v[48:63], v[184:187], v[202:205], v[48:63]
	ds_read_b64_tr_b16 v[202:203], v227 offset:0x5400
	ds_read_b64_tr_b16 v[204:205], v227 offset:0x5c00
	v_mfma_f32_32x32x16_bf16 v[48:63], v[188:191], v[206:209], v[48:63]
	ds_read_b64_tr_b16 v[206:207], v227 offset:0x6400
	ds_read_b64_tr_b16 v[208:209], v227 offset:0x6c00
	v_mfma_f32_32x32x16_bf16 v[48:63], v[192:195], v[210:213], v[48:63]
	ds_read_b64_tr_b16 v[210:211], v227 offset:0x7400
	ds_read_b64_tr_b16 v[212:213], v227 offset:0x7c00
	s_waitcnt lgkmcnt(0)
	v_mfma_f32_32x32x16_bf16 v[32:47], v[180:183], v[196:199], v[32:47]
	ds_read_b64_tr_b16 v[196:197], v227 offset:0x4600
	ds_read_b64_tr_b16 v[198:199], v227 offset:0x4e00
	v_mfma_f32_32x32x16_bf16 v[32:47], v[184:187], v[202:205], v[32:47]
	ds_read_b64_tr_b16 v[202:203], v227 offset:0x5600
	ds_read_b64_tr_b16 v[204:205], v227 offset:0x5e00
	v_mfma_f32_32x32x16_bf16 v[32:47], v[188:191], v[206:209], v[32:47]
	ds_read_b64_tr_b16 v[206:207], v227 offset:0x6600
	ds_read_b64_tr_b16 v[208:209], v227 offset:0x6e00
	v_mfma_f32_32x32x16_bf16 v[32:47], v[192:195], v[210:213], v[32:47]
	ds_read_b64_tr_b16 v[210:211], v227 offset:0x7600
	ds_read_b64_tr_b16 v[212:213], v227 offset:0x7e00
	s_waitcnt lgkmcnt(0)
	s_cmp_le_i32 s4, s57
	s_cselect_b64 s[4:5], -1, 0
	s_cmp_gt_i32 s69, s58
	s_cselect_b64 s[72:73], -1, 0
	s_and_b64 s[4:5], s[4:5], s[72:73]
	s_and_b64 vcc, exec, s[4:5]
	s_cbranch_vccz .Lattn_h2_pv_slow
	v_mfma_f32_32x32x16_bf16 v[16:31], v[180:183], v[196:199], v[16:31]
	v_max_f32_e32 v0, v129, v129
	v_max_f32_e32 v180, v128, v128
	v_max_f32_e32 v0, v180, v0
	v_max3_f32 v0, v0, v130, v131
	v_max3_f32 v0, v0, v132, v133
	v_max3_f32 v0, v0, v134, v135
	v_mfma_f32_32x32x16_bf16 v[16:31], v[184:187], v[202:205], v[16:31]
	v_max3_f32 v0, v0, v136, v137
	v_max3_f32 v0, v0, v138, v139
	v_max3_f32 v0, v0, v140, v141
	v_max3_f32 v0, v0, v142, v143
	v_max3_f32 v0, v0, v112, v113
	v_max3_f32 v0, v0, v114, v115
	v_mfma_f32_32x32x16_bf16 v[16:31], v[188:191], v[206:209], v[16:31]
	v_max3_f32 v0, v0, v116, v117
	v_max3_f32 v0, v0, v118, v119
	v_max3_f32 v0, v0, v120, v121
	v_max3_f32 v0, v0, v122, v123
	v_max3_f32 v0, v0, v124, v125
	v_max3_f32 v0, v0, v126, v127
	v_mov_b32_e32 v180, v0
	v_mfma_f32_32x32x16_bf16 v[16:31], v[192:195], v[210:213], v[16:31]
	s_nop 0
	v_permlane32_swap_b32_e32 v0, v180
	v_max_f32_e32 v180, v180, v180
	v_max_f32_e32 v0, v0, v0
	v_max_f32_e32 v0, v0, v180
	v_sub_f32_e32 v180, v0, v247
	v_mul_f32_e32 v180, 0x3db504f3, v180
	v_cmp_ge_f32_e32 vcc, s83, v180
	s_cmp_eq_u64 vcc, exec
	s_cselect_b64 s[4:5], -1, 0
	s_andn2_b64 vcc, exec, s[28:29]
	s_branch .Lattn_h2_b1
; __device__ __forceinline__ void mask_tile(f32x16& p0, f32x16& p1, int dq, unsigned W) {
;     const float NEG = -__builtin_inff();
; #pragma unroll
;     for (int r = 0; r < 16; ++r) {
;         const int c = (r & 3) + 8 * (r >> 2);
;         if ((unsigned)(dq - c) >= W) p0[r] = NEG;
;         if ((unsigned)(dq - c - 32) >= W) p1[r] = NEG;
;     }
; }
; template <int VB, bool SK>
; __device__ __forceinline__ void pv_tile(f32x16* o, int vb0, bf16x8 pa0, bf16x8 pa1, bf16x8 pa2, bf16x8 pa3, bool act) {
;     if (SK && !act) return;
;     ...
;     PV_D0(0); PV_D0(1); PV_D0(2); PV_D0(3);
.Lattn_h2_pv_slow:
	v_mfma_f32_32x32x16_bf16 v[16:31], v[180:183], v[196:199], v[16:31]
	v_mfma_f32_32x32x16_bf16 v[16:31], v[184:187], v[202:205], v[16:31]
	v_mfma_f32_32x32x16_bf16 v[16:31], v[188:191], v[206:209], v[16:31]
	v_mfma_f32_32x32x16_bf16 v[16:31], v[192:195], v[210:213], v[16:31]
	v_add_u32_e32 v0, 0x103b, v243
	v_cmp_gt_u32_e32 vcc, s81, v0
	v_add_u32_e32 v0, 27, v243
	s_nop 0
	v_cndmask_b32_e32 v128, v216, v128, vcc
	v_cmp_lt_u32_e32 vcc, s82, v0
	v_add_u32_e32 v0, 58, v243
	s_nop 0
	v_cndmask_b32_e32 v112, v216, v112, vcc
	v_cmp_lt_u32_e32 vcc, s82, v0
	v_add_u32_e32 v0, 26, v243
	s_nop 0
	v_cndmask_b32_e32 v129, v216, v129, vcc
	v_cmp_lt_u32_e32 vcc, s82, v0
	v_add_u32_e32 v0, 57, v243
	s_nop 0
	v_cndmask_b32_e32 v113, v216, v113, vcc
	v_cmp_lt_u32_e32 vcc, s82, v0
	v_add_u32_e32 v0, 25, v243
	s_nop 0
	v_cndmask_b32_e32 v130, v216, v130, vcc
	v_cmp_lt_u32_e32 vcc, s82, v0
	v_add_u32_e32 v0, 56, v243
	s_nop 0
	v_cndmask_b32_e32 v114, v216, v114, vcc
	v_cmp_lt_u32_e32 vcc, s82, v0
	v_add_u32_e32 v0, 24, v243
	s_nop 0
	v_cndmask_b32_e32 v131, v216, v131, vcc
	v_cmp_lt_u32_e32 vcc, s82, v0
	v_add_u32_e32 v0, 51, v243
	s_nop 0
	v_cndmask_b32_e32 v115, v216, v115, vcc
	v_cmp_lt_u32_e32 vcc, s82, v0
	v_add_u32_e32 v0, 19, v243
	s_nop 0
	v_cndmask_b32_e32 v132, v216, v132, vcc
	v_cmp_lt_u32_e32 vcc, s82, v0
	v_add_u32_e32 v0, 50, v243
	s_nop 0
	v_cndmask_b32_e32 v116, v216, v116, vcc
	v_cmp_lt_u32_e32 vcc, s82, v0
	v_add_u32_e32 v0, 18, v243
	s_nop 0
	v_cndmask_b32_e32 v133, v216, v133, vcc
	v_cmp_lt_u32_e32 vcc, s82, v0
	v_add_u32_e32 v0, 49, v243
	s_nop 0
	v_cndmask_b32_e32 v117, v216, v117, vcc
	v_cmp_lt_u32_e32 vcc, s82, v0
	v_add_u32_e32 v0, 17, v243
	s_nop 0
	v_cndmask_b32_e32 v134, v216, v134, vcc
	v_cmp_lt_u32_e32 vcc, s82, v0
	v_add_u32_e32 v0, 48, v243
	s_nop 0
	v_cndmask_b32_e32 v118, v216, v118, vcc
	v_cmp_lt_u32_e32 vcc, s82, v0
	v_add_u32_e32 v0, 16, v243
	s_nop 0
	v_cndmask_b32_e32 v135, v216, v135, vcc
	v_cmp_lt_u32_e32 vcc, s82, v0
	v_add_u32_e32 v0, 43, v243
	s_nop 0
	v_cndmask_b32_e32 v119, v216, v119, vcc
	v_cmp_lt_u32_e32 vcc, s82, v0
	v_add_u32_e32 v0, 11, v243
	s_nop 0
	v_cndmask_b32_e32 v136, v216, v136, vcc
	v_cmp_lt_u32_e32 vcc, s82, v0
	v_add_u32_e32 v0, 42, v243
	s_nop 0
	v_cndmask_b32_e32 v120, v216, v120, vcc
	v_cmp_lt_u32_e32 vcc, s82, v0
	v_add_u32_e32 v0, 10, v243
	s_nop 0
	v_cndmask_b32_e32 v137, v216, v137, vcc
	v_cmp_lt_u32_e32 vcc, s82, v0
	v_add_u32_e32 v0, 41, v243
	s_nop 0
	v_cndmask_b32_e32 v121, v216, v121, vcc
	v_cmp_lt_u32_e32 vcc, s82, v0
	v_add_u32_e32 v0, 9, v243
	s_nop 0
	v_cndmask_b32_e32 v138, v216, v138, vcc
	v_cmp_lt_u32_e32 vcc, s82, v0
	v_add_u32_e32 v0, 40, v243
	s_nop 0
	v_cndmask_b32_e32 v122, v216, v122, vcc
	v_cmp_lt_u32_e32 vcc, s82, v0
	v_add_u32_e32 v0, 8, v243
	s_nop 0
	v_cndmask_b32_e32 v139, v216, v139, vcc
	v_cmp_lt_u32_e32 vcc, s82, v0
	v_add_u32_e32 v0, 35, v243
	s_nop 0
	v_cndmask_b32_e32 v123, v216, v123, vcc
	v_cmp_lt_u32_e32 vcc, s82, v0
	v_add_u32_e32 v0, 3, v243
	s_nop 0
	v_cndmask_b32_e32 v140, v216, v140, vcc
	v_cmp_lt_u32_e32 vcc, s82, v0
	v_add_u32_e32 v0, 34, v243
	s_nop 0
	v_cndmask_b32_e32 v124, v216, v124, vcc
	v_cmp_lt_u32_e32 vcc, s82, v0
	v_add_u32_e32 v0, 2, v243
	s_nop 0
	v_cndmask_b32_e32 v141, v216, v141, vcc
	v_cmp_lt_u32_e32 vcc, s82, v0
	v_add_u32_e32 v0, 33, v243
	s_nop 0
	v_cndmask_b32_e32 v125, v216, v125, vcc
	v_cmp_lt_u32_e32 vcc, s82, v0
	v_add_u32_e32 v0, 1, v243
	s_nop 0
	v_cndmask_b32_e32 v142, v216, v142, vcc
	v_cmp_lt_u32_e32 vcc, s82, v0
	v_add_u32_e32 v0, 32, v243
	s_nop 0
	v_cndmask_b32_e32 v126, v216, v126, vcc
	v_cmp_lt_u32_e32 vcc, s82, v0
	s_nop 1
	v_cndmask_b32_e32 v143, v216, v143, vcc
	v_cmp_lt_u32_e32 vcc, s82, v243
	s_nop 1
	v_cndmask_b32_e32 v127, v216, v127, vcc

.Lattn_h2_b1:
	s_barrier
	s_cbranch_vccnz .LBB0_1259
	s_waitcnt vmcnt(0)
	s_waitcnt vmcnt(3)
	ds_write_b128 v237, v[2:5] offset:16384
	s_waitcnt vmcnt(2)
	ds_write_b128 v238, v[6:9] offset:16384
	ds_write_b32 v242, v246 offset:256
	s_waitcnt vmcnt(1)
	ds_write_b128 v222, v[10:13] offset:49152
	s_waitcnt vmcnt(0)
	ds_write_b128 v222, v[176:179] offset:57344
